# SGU task strips permuted so the 8 strips of a 128-token chunk run on one XCD (L2 reuse of the chunk's vn)
# speedup vs baseline: 1.0079x; 1.0079x over previous
; #define KIN(i) (*(const float* const __attribute__((address_space(4)))*)(kp + 8 * (i)))
; __device__ __forceinline__ void p4_sgu_task(const bf16_t* Wsgu, const bf16_t* VT, const bf16_t* U, const float* sgu_b, bf16_t* MIX, int strip, int h, int lane) {
;     const int fr = lane & 15, fq = lane >> 4;
;     const int tok0 = strip * 16, cmask = tok0 < TP ? 127 : 63, t0 = tok0 & cmask, cstart = tok0 - t0;
;     const int nks = (t0 + 16 + 31) >> 5;
;     f32x4 acc[8];
; #pragma unroll
;     for (int i = 0; i < 8; ++i) acc[i] = (f32x4){0.f, 0.f, 0.f, 0.f};
;     const bf16_t* wrow = Wsgu + ((size_t)h * 128 + t0 + fr) * 128 + 8 * fq;
;     for (int kk = 0; kk < nks; ++kk) {
;         const bf16x8 a = *(const bf16x8*)(wrow + 32 * kk);
;         const int sabs = cstart + 32 * kk;
;         const bf16_t* vb = VT + (((size_t)(sabs >> 6) * 8 + h) * 128 + fr) * 64 + (sabs & 63) + 8 * fq;
; #pragma unroll
;         for (int nf = 0; nf < 8; ++nf) { const bf16x8 b = *(const bf16x8*)(vb + (size_t)(16 * nf) * 64); acc[nf] = __builtin_amdgcn_mfma_f32_16x16x32_bf16(b, a, acc[nf], 0, 0, 0); }
;     }
; __global__ void __launch_bounds__(NTHREADS, 2) fwd_megakernel(Args args) {
;     ...
;             else { const int r = it - NPOOL; p4_sgu_task(Wsgu, VT, U, KIN(11), MIX, r >> 3, r & 7, lane); }
.LBB0_674:
	s_cmpk_gt_i32 s3, 0x11ff
	s_mov_b64 s[8:9], -1
	s_cbranch_scc0 .LBB0_678
	s_add_i32 s11, s3, 0xffffee00
	s_load_dwordx2 s[8:9], s[12:13], 0x58
	s_bfe_u32 s10, s11, 0x30003
	s_bfe_u32 s22, s11, 0x30006
	s_andn2_b32 s11, s11, 0x1f8
	s_lshl_b32 s10, s10, 6
	s_lshl_b32 s22, s22, 3
	s_or_b32 s11, s11, s10
	s_or_b32 s11, s11, s22
	s_lshl_b32 s10, s11, 1
	s_cmpk_lt_u32 s11, 0x2000
	s_cselect_b32 s11, 0x70, 48
	s_and_b32 s11, s11, s10
	s_and_b32 s22, s10, 0x7ffffff0
	s_add_i32 s27, s11, 47
	s_lshr_b32 s33, s27, 5
	s_lshl_b32 s27, s3, 7
	s_and_b32 s27, s27, 0x380
	s_sub_i32 s34, s22, s11
	s_lshl_b32 s42, s7, 8
	s_and_b32 s42, s42, 0x38000
	v_or_b32_e32 v216, s22, v63
	v_mov_b32_e32 v217, 0
	v_or_b32_e32 v246, s27, v148
	v_lshlrev_b32_e32 v246, 1, v246
	v_mov_b32_e32 v247, 0
	v_lshlrev_b64 v[242:243], 11, v[216:217]
	v_lshl_add_u64 v[242:243], s[20:21], 0, v[242:243]
	v_lshl_add_u64 v[242:243], v[242:243], 0, v[246:247]
	global_load_dwordx2 v[224:225], v[242:243], off
	global_load_dwordx2 v[226:227], v[242:243], off offset:32
	global_load_dwordx2 v[228:229], v[242:243], off offset:64
	global_load_dwordx2 v[230:231], v[242:243], off offset:96
	global_load_dwordx2 v[232:233], v[242:243], off offset:128
	global_load_dwordx2 v[234:235], v[242:243], off offset:160
	global_load_dwordx2 v[236:237], v[242:243], off offset:192
	global_load_dwordx2 v[238:239], v[242:243], off offset:224
	v_lshlrev_b64 v[244:245], 12, v[216:217]
	v_lshl_add_u64 v[244:245], s[16:17], 0, v[244:245]
	v_lshl_add_u64 v[244:245], v[244:245], 0, v[246:247]
	v_or_b32_e32 v36, s27, v63
	v_or_b32_e32 v240, s11, v36
	v_lshlrev_b32_e32 v240, 2, v240
	v_lshlrev_b32_e32 v60, 7, v36
	v_lshl_add_u64 v[32:33], s[14:15], 0, v[60:61]
	v_or_b32_e32 v0, s11, v63
	v_lshl_or_b32 v60, v0, 8, s42
	v_lshl_add_u64 v[34:35], v[80:81], 0, v[60:61]
	s_waitcnt lgkmcnt(0)
	global_load_dword v240, v240, s[8:9]
	s_ashr_i32 s42, s34, 6
	s_ashr_i32 s43, s42, 31
	s_and_b32 s22, s34, 48
	s_lshl_b64 s[42:43], s[42:43], 17
	s_lshl_b32 s22, s22, 1
	v_lshl_add_u64 v[210:211], v[32:33], 0, s[42:43]
	v_lshl_add_u64 v[210:211], v[210:211], 0, s[22:23]
	v_lshl_add_u64 v[210:211], v[210:211], 0, v[82:83]
	s_mov_b32 s42, 0x2000
	s_mov_b32 s43, 0
	global_load_dwordx4 v[158:161], v[34:35], off
	v_lshl_add_u64 v[212:213], v[210:211], 0, s[42:43]
	s_mov_b32 s42, 0x3000
	global_load_dwordx4 v[162:165], v[210:211], off
	global_load_dwordx4 v[166:169], v[210:211], off offset:2048
	v_lshl_add_u64 v[214:215], v[210:211], 0, s[42:43]
	global_load_dwordx4 v[170:173], v[212:213], off offset:-4096
	global_load_dwordx4 v[174:177], v[212:213], off offset:-2048
	global_load_dwordx4 v[178:181], v[212:213], off
	global_load_dwordx4 v[182:185], v[212:213], off offset:2048
	global_load_dwordx4 v[186:189], v[214:215], off
	global_load_dwordx4 v[190:193], v[214:215], off offset:2048
	s_add_i32 s34, s34, 32
	v_lshl_add_u64 v[34:35], v[34:35], 0, 64
	v_mov_b32_e32 v0, 0
	v_mov_b32_e32 v1, 0
	v_mov_b32_e32 v2, 0
	v_mov_b32_e32 v3, 0
	v_mov_b32_e32 v4, 0
	v_mov_b32_e32 v5, 0
	v_mov_b32_e32 v6, 0
	v_mov_b32_e32 v7, 0
	v_mov_b32_e32 v8, 0
	v_mov_b32_e32 v9, 0
	v_mov_b32_e32 v10, 0
	v_mov_b32_e32 v11, 0
	v_mov_b32_e32 v12, 0
	v_mov_b32_e32 v13, 0
	v_mov_b32_e32 v14, 0
	v_mov_b32_e32 v15, 0
	v_mov_b32_e32 v16, 0
	v_mov_b32_e32 v17, 0
	v_mov_b32_e32 v18, 0
	v_mov_b32_e32 v19, 0
	v_mov_b32_e32 v20, 0
	v_mov_b32_e32 v21, 0
	v_mov_b32_e32 v22, 0
	v_mov_b32_e32 v23, 0
	v_mov_b32_e32 v24, 0
	v_mov_b32_e32 v25, 0
	v_mov_b32_e32 v26, 0
	v_mov_b32_e32 v27, 0
	v_mov_b32_e32 v28, 0
	v_mov_b32_e32 v29, 0
	v_mov_b32_e32 v30, 0
	v_mov_b32_e32 v31, 0
